# attention: QK MFMA accumulates onto -m_ref tuples (no per-element subtract in lazy fast path), V fragment reads issued at fast-path start, simpler overflow check
# speedup vs baseline: 1.0065x; 1.0065x over previous
.LBB0_812:
	s_lshl_b32 s10, s10, 6
	v_lshlrev_b64 v[14:15], 9, v[14:15]
	v_lshl_add_u64 v[14:15], s[28:29], 0, v[14:15]
	s_lshl_b32 s26, s10, 1
	v_lshl_add_u64 v[14:15], v[14:15], 0, s[26:27]
	v_mov_b32_e32 v5, v163
	v_lshl_add_u64 v[14:15], v[14:15], 0, v[4:5]
	global_load_dwordx4 v[136:139], v[14:15], off
	global_load_dwordx4 v[140:143], v[14:15], off offset:256
	v_and_b32_e32 v145, 63, v17
	s_waitcnt vmcnt(0)
	v_mul_f32_e32 v158, 0x3fb8aa3b, v1
	v_and_b32_e32 v1, 7, v17
	v_and_b32_e32 v15, 64, v204
	s_movk_i32 s12, 0x840
	v_lshlrev_b32_e32 v176, 3, v18
	s_movk_i32 s10, 0x90
	v_xor_b32_e32 v14, 32, v204
	v_lshl_add_u64 v[8:9], v[10:11], 0, v[8:9]
	v_mul_u32_u24_e32 v10, 0x108, v16
	v_cmp_gt_u32_e32 vcc, 32, v145
	v_lshlrev_b32_e32 v144, 4, v1
	v_mul_u32_u24_e32 v185, 0x840, v1
	v_mad_u32_u24 v1, v1, s12, 0
	v_add_u32_e32 v11, 64, v15
	v_readlane_b32 s12, v243, 49
	s_cmp_eq_u32 s11, 31
	v_mul_lo_u32 v177, v2, s10
	v_lshlrev_b32_e32 v178, 1, v2
	v_mul_lo_u32 v179, v6, s10
	v_lshlrev_b32_e32 v181, 1, v6
	v_mul_u32_u24_e32 v182, 0x90, v16
	v_cndmask_b32_e64 v148, 0, 1.0, vcc
	v_add3_u32 v186, v10, v176, s12
	v_cmp_lt_i32_e32 vcc, v14, v11
	s_cselect_b32 s11, 3, 2
	s_add_u32 s12, s28, s26
	v_lshl_add_u64 v[150:151], v[12:13], 0, v[2:3]
	v_mov_b32_e32 v32, v163
	v_mov_b32_e32 v33, v163
	v_mov_b32_e32 v46, v163
	v_lshl_add_u64 v[152:153], v[8:9], 0, v[2:3]
	v_lshl_add_u64 v[154:155], v[8:9], 0, v[6:7]
	v_add3_u32 v187, v182, v0, 0
	v_add3_u32 v0, 0, v177, v144
	v_add_u32_e32 v2, v1, v178
	v_add3_u32 v3, 0, v179, v144
	v_add_u32_e32 v1, v1, v181
	v_cndmask_b32_e32 v6, v204, v14, vcc
	s_addc_u32 s13, s29, 0
	v_mov_b32_e32 v47, v163
	v_lshlrev_b32_e32 v183, 2, v18
	v_mov_b32_e32 v34, v163
	v_mov_b32_e32 v35, v163
	v_mov_b32_e32 v36, v163
	v_mov_b32_e32 v37, v163
	v_mov_b32_e32 v38, v163
	v_mov_b32_e32 v39, v163
	v_mov_b32_e32 v40, v163
	v_mov_b32_e32 v41, v163
	v_mov_b32_e32 v42, v163
	v_mov_b32_e32 v43, v163
	v_mov_b32_e32 v44, v163
	v_mov_b32_e32 v45, v163
	ds_write_b128 v0, v[128:131]
	ds_write_b16 v2, v132 offset:18432
	ds_write_b16_d16_hi v2, v132 offset:18696
	ds_write_b16 v2, v133 offset:18960
	ds_write_b16_d16_hi v2, v133 offset:19224
	ds_write_b16 v2, v134 offset:19488
	ds_write_b16_d16_hi v2, v134 offset:19752
	ds_write_b16 v2, v135 offset:20016
	ds_write_b16_d16_hi v2, v135 offset:20280
	v_lshlrev_b32_e32 v180, 2, v6
	v_lshl_add_u64 v[156:157], s[12:13], 0, v[4:5]
	v_mov_b64_e32 v[16:17], v[32:33]
	v_mov_b64_e32 v[62:63], v[46:47]
	s_mov_b32 s10, 0
	v_or_b32_e32 v184, 32, v162
	v_mov_b32_e32 v149, v148
	v_mov_b32_e32 v159, v158
	v_mul_f32_e32 v206, -1.0, v158
	v_mov_b32_e32 v207, v206
	v_mov_b32_e32 v208, v206
	v_mov_b32_e32 v209, v206
	v_mov_b32_e32 v210, v206
	v_mov_b32_e32 v211, v206
	v_mov_b32_e32 v212, v206
	v_mov_b32_e32 v213, v206
	v_mov_b32_e32 v214, v206
	v_mov_b32_e32 v215, v206
	v_mov_b32_e32 v216, v206
	v_mov_b32_e32 v217, v206
	v_mov_b32_e32 v218, v206
	v_mov_b32_e32 v219, v206
	v_mov_b32_e32 v220, v206
	v_mov_b32_e32 v221, v206
	v_mov_b32_e32 v222, v206
	v_mov_b32_e32 v223, v206
	v_mov_b32_e32 v224, v206
	v_mov_b32_e32 v225, v206
	v_mov_b32_e32 v226, v206
	v_mov_b32_e32 v227, v206
	v_mov_b32_e32 v228, v206
	v_mov_b32_e32 v229, v206
	v_mov_b32_e32 v230, v206
	v_mov_b32_e32 v231, v206
	v_mov_b32_e32 v232, v206
	v_mov_b32_e32 v233, v206
	v_mov_b32_e32 v234, v206
	v_mov_b32_e32 v235, v206
	v_mov_b32_e32 v236, v206
	v_mov_b32_e32 v237, v206
	v_mov_b64_e32 v[18:19], v[34:35]
	v_mov_b64_e32 v[20:21], v[36:37]
	v_mov_b64_e32 v[22:23], v[38:39]
	v_mov_b64_e32 v[24:25], v[40:41]
	v_mov_b64_e32 v[26:27], v[42:43]
	v_mov_b64_e32 v[28:29], v[44:45]
	v_mov_b64_e32 v[30:31], v[46:47]
	v_mov_b64_e32 v[60:61], v[44:45]
	v_mov_b64_e32 v[58:59], v[42:43]
	v_mov_b64_e32 v[56:57], v[40:41]
	v_mov_b64_e32 v[54:55], v[38:39]
	v_mov_b64_e32 v[52:53], v[36:37]
	v_mov_b64_e32 v[50:51], v[34:35]
	ds_write_b128 v3, v[136:139]
	ds_write_b16 v1, v140 offset:18432
	ds_write_b16_d16_hi v1, v140 offset:18696
	ds_write_b16 v1, v141 offset:18960
	ds_write_b16_d16_hi v1, v141 offset:19224
	ds_write_b16 v1, v142 offset:19488
	ds_write_b16_d16_hi v1, v142 offset:19752
	ds_write_b16 v1, v143 offset:20016
	ds_write_b16_d16_hi v1, v143 offset:20280
	v_mov_b64_e32 v[0:1], v[32:33]
	v_mov_b64_e32 v[48:49], v[32:33]
	v_mov_b64_e32 v[2:3], v[34:35]
	v_mov_b64_e32 v[4:5], v[36:37]
	v_mov_b64_e32 v[6:7], v[38:39]
	v_mov_b64_e32 v[8:9], v[40:41]
	v_mov_b64_e32 v[10:11], v[42:43]
	v_mov_b64_e32 v[12:13], v[44:45]
	v_mov_b64_e32 v[14:15], v[46:47]
	s_waitcnt lgkmcnt(0)
	s_barrier

.Latt_noskip:
	s_setprio 1
	ds_read_b128 v[64:67], v189
	ds_read_b128 v[164:167], v189 offset:32
	ds_read_b128 v[168:171], v189 offset:64
	ds_read_b128 v[172:175], v189 offset:96
	s_waitcnt lgkmcnt(3)
	v_mfma_f32_32x32x16_bf16 v[80:95], v[64:67], v[96:99], v[206:221]
	v_mfma_f32_32x32x16_bf16 v[64:79], v[64:67], v[112:115], v[222:237]
	s_waitcnt lgkmcnt(2)
	v_mfma_f32_32x32x16_bf16 v[80:95], v[164:167], v[100:103], v[80:95]
	v_mfma_f32_32x32x16_bf16 v[64:79], v[164:167], v[116:119], v[64:79]
	s_waitcnt lgkmcnt(1)
	v_mfma_f32_32x32x16_bf16 v[80:95], v[168:171], v[104:107], v[80:95]
	v_mfma_f32_32x32x16_bf16 v[64:79], v[168:171], v[120:123], v[64:79]
	s_waitcnt lgkmcnt(0)
	v_mfma_f32_32x32x16_bf16 v[80:95], v[172:175], v[108:111], v[80:95]
	v_mfma_f32_32x32x16_bf16 v[64:79], v[172:175], v[124:127], v[64:79]
	s_setprio 0
	s_cmp_lt_i32 s9, 2
	s_cbranch_scc1 .LBB0_818
	s_cmp_eq_u32 s9, 2
	s_cselect_b64 s[50:51], -1, 0
	s_cbranch_execz .LBB0_819
	s_branch .LBB0_820

.LBB0_822:
	s_nop 2
	v_max_f32_e32 v168, v80, v81
	v_max_f32_e32 v169, v64, v65
	v_max3_f32 v168, v168, v82, v83
	v_max3_f32 v169, v169, v66, v67
	v_max3_f32 v168, v168, v84, v85
	v_max3_f32 v169, v169, v68, v69
	v_max3_f32 v168, v168, v86, v87
	v_max3_f32 v169, v169, v70, v71
	v_max3_f32 v168, v168, v88, v89
	v_max3_f32 v169, v169, v72, v73
	v_max3_f32 v168, v168, v90, v91
	v_max3_f32 v169, v169, v74, v75
	v_max3_f32 v168, v168, v92, v93
	v_max3_f32 v169, v169, v76, v77
	v_max3_f32 v168, v168, v94, v95
	v_max3_f32 v169, v169, v78, v79
	v_max_f32_e32 v168, v168, v169
	v_cmp_lt_f32_e32 vcc, 0x41000000, v168
	s_cbranch_vccnz .Latt_slow
	ds_read2_b64 v[164:167], v188 offset1:2
	v_add_u32_e32 v201, 0x2000, v188
	ds_read2_b64 v[168:171], v201 offset0:32 offset1:34
	ds_read2_b64 v[172:175], v188 offset0:4 offset1:6
	ds_read2_b64 v[238:241], v201 offset0:36 offset1:38
	v_exp_f32_e32 v80, v80
	v_exp_f32_e32 v64, v64
	v_exp_f32_e32 v81, v81
	v_exp_f32_e32 v65, v65
	v_exp_f32_e32 v82, v82
	v_exp_f32_e32 v66, v66
	v_exp_f32_e32 v83, v83
	v_exp_f32_e32 v67, v67
	v_exp_f32_e32 v84, v84
	v_exp_f32_e32 v68, v68
	v_exp_f32_e32 v85, v85
	v_exp_f32_e32 v69, v69
	v_exp_f32_e32 v86, v86
	v_exp_f32_e32 v70, v70
	v_exp_f32_e32 v87, v87
	v_exp_f32_e32 v71, v71
	v_exp_f32_e32 v88, v88
	v_exp_f32_e32 v72, v72
	v_exp_f32_e32 v89, v89
	v_exp_f32_e32 v73, v73
	v_exp_f32_e32 v90, v90
	v_exp_f32_e32 v74, v74
	v_exp_f32_e32 v91, v91
	v_exp_f32_e32 v75, v75
	v_exp_f32_e32 v92, v92
	v_exp_f32_e32 v76, v76
	v_exp_f32_e32 v93, v93
	v_exp_f32_e32 v77, v77
	v_exp_f32_e32 v94, v94
	v_exp_f32_e32 v78, v78
	v_exp_f32_e32 v95, v95
	v_exp_f32_e32 v79, v79
	v_add_f32_e32 v197, v80, v81
	v_add_f32_e32 v198, v64, v65
	v_add_f32_e32 v197, v197, v82
	v_add_f32_e32 v198, v198, v66
	v_add_f32_e32 v197, v197, v83
	v_add_f32_e32 v198, v198, v67
	v_add_f32_e32 v197, v197, v84
	v_add_f32_e32 v198, v198, v68
	v_add_f32_e32 v197, v197, v85
	v_add_f32_e32 v198, v198, v69
	v_add_f32_e32 v197, v197, v86
	v_add_f32_e32 v198, v198, v70
	v_add_f32_e32 v197, v197, v87
	v_add_f32_e32 v198, v198, v71
	v_add_f32_e32 v197, v197, v88
	v_add_f32_e32 v198, v198, v72
	v_add_f32_e32 v197, v197, v89
	v_add_f32_e32 v198, v198, v73
	v_add_f32_e32 v197, v197, v90
	v_add_f32_e32 v198, v198, v74
	v_add_f32_e32 v197, v197, v91
	v_add_f32_e32 v198, v198, v75
	v_add_f32_e32 v197, v197, v92
	v_add_f32_e32 v198, v198, v76
	v_add_f32_e32 v197, v197, v93
	v_add_f32_e32 v198, v198, v77
	v_add_f32_e32 v197, v197, v94
	v_add_f32_e32 v198, v198, v78
	v_add_f32_e32 v197, v197, v95
	v_add_f32_e32 v198, v198, v79
	v_add_f32_e32 v149, v149, v197
	v_add_f32_e32 v148, v148, v198
	v_cvt_pk_bf16_f32 v80, v80, v81
	v_cvt_pk_bf16_f32 v81, v82, v83
	v_cvt_pk_bf16_f32 v82, v84, v85
	v_cvt_pk_bf16_f32 v83, v86, v87
	v_cvt_pk_bf16_f32 v84, v88, v89
	v_cvt_pk_bf16_f32 v85, v90, v91
	v_cvt_pk_bf16_f32 v86, v92, v93
	v_cvt_pk_bf16_f32 v87, v94, v95
	v_cvt_pk_bf16_f32 v64, v64, v65
	v_cvt_pk_bf16_f32 v65, v66, v67
	v_cvt_pk_bf16_f32 v66, v68, v69
	v_cvt_pk_bf16_f32 v67, v70, v71
	v_cvt_pk_bf16_f32 v68, v72, v73
	v_cvt_pk_bf16_f32 v69, v74, v75
	v_cvt_pk_bf16_f32 v70, v76, v77
	v_cvt_pk_bf16_f32 v71, v78, v79
	v_mov_b32_e32 v190, v159
	v_mov_b32_e32 v191, v158
	s_branch .Latt_pv
.Latt_slow:
	v_mov_b32_e32 v199, v159
	v_mov_b32_e32 v200, v158
	v_mov_b32_e32 v159, 0
	v_mov_b32_e32 v158, 0
	v_max_f32_e32 v164, v81, v81
	v_max_f32_e32 v165, v80, v80
	v_max_f32_e32 v164, v165, v164
	v_max3_f32 v164, v164, v82, v83
	v_max3_f32 v164, v164, v84, v85
	v_max3_f32 v164, v164, v86, v87
	v_max3_f32 v164, v164, v88, v89
	v_max3_f32 v164, v164, v90, v91
	v_max3_f32 v164, v164, v92, v93
	v_max3_f32 v164, v164, v94, v95
	v_mov_b32_e32 v165, v164
	s_nop 1
	v_permlane32_swap_b32_e32 v164, v165
	v_max3_f32 v190, v159, v164, v165
	v_sub_f32_e32 v80, v80, v190
	v_sub_f32_e32 v81, v81, v190
	v_exp_f32_e32 v80, v80
	v_sub_f32_e32 v82, v82, v190
	v_exp_f32_e32 v81, v81
	v_sub_f32_e32 v83, v83, v190
	v_exp_f32_e32 v82, v82
	v_exp_f32_e32 v83, v83
	v_sub_f32_e32 v84, v84, v190
	v_sub_f32_e32 v164, v159, v190
	v_add_f32_e32 v159, 0, v80
	v_exp_f32_e32 v84, v84
	v_add_f32_e32 v159, v81, v159
	v_add_f32_e32 v159, v82, v159
	v_sub_f32_e32 v85, v85, v190
	v_add_f32_e32 v159, v83, v159
	v_exp_f32_e32 v85, v85
	v_add_f32_e32 v159, v84, v159
	v_cvt_pk_bf16_f32 v80, v80, v81
	v_cvt_pk_bf16_f32 v81, v82, v83
	v_cvt_pk_bf16_f32 v82, v84, v85
	v_max_f32_e32 v83, v65, v65
	v_max_f32_e32 v84, v64, v64
	v_max_f32_e32 v83, v84, v83
	v_max3_f32 v83, v83, v66, v67
	v_max3_f32 v83, v83, v68, v69
	v_max3_f32 v83, v83, v70, v71
	v_sub_f32_e32 v86, v86, v190
	v_max3_f32 v83, v83, v72, v73
	v_exp_f32_e32 v165, v86
	v_sub_f32_e32 v86, v87, v190
	v_max3_f32 v83, v83, v74, v75
	v_exp_f32_e32 v169, v86
	v_sub_f32_e32 v86, v88, v190
	v_max3_f32 v83, v83, v76, v77
	v_add_f32_e32 v193, v85, v159
	v_exp_f32_e32 v159, v86
	v_sub_f32_e32 v86, v89, v190
	v_max3_f32 v88, v83, v78, v79
	v_exp_f32_e32 v89, v86
	v_sub_f32_e32 v86, v90, v190
	v_mov_b32_e32 v90, v88
	v_exp_f32_e32 v167, v86
	v_sub_f32_e32 v86, v91, v190
	v_permlane32_swap_b32_e32 v88, v90
	v_exp_f32_e32 v91, v164
	v_exp_f32_e32 v171, v86
	v_max3_f32 v191, v158, v88, v90
	v_sub_f32_e32 v64, v64, v191
	v_exp_f32_e32 v194, v64
	v_sub_f32_e32 v64, v65, v191
	v_exp_f32_e32 v195, v64
	v_sub_f32_e32 v64, v66, v191
	v_exp_f32_e32 v196, v64
	v_sub_f32_e32 v64, v67, v191
	v_exp_f32_e32 v67, v64
	v_sub_f32_e32 v65, v68, v191
	v_add_f32_e32 v64, 0, v194
	v_exp_f32_e32 v68, v65
	v_sub_f32_e32 v65, v69, v191
	v_add_f32_e32 v64, v195, v64
	v_exp_f32_e32 v69, v65
	v_sub_f32_e32 v65, v70, v191
	v_add_f32_e32 v64, v196, v64
	v_exp_f32_e32 v164, v65
	v_sub_f32_e32 v65, v71, v191
	v_add_f32_e32 v64, v67, v64
	v_exp_f32_e32 v168, v65
	v_sub_f32_e32 v66, v72, v191
	v_sub_f32_e32 v90, v158, v191
	v_add_f32_e32 v64, v68, v64
	v_exp_f32_e32 v158, v66
	v_sub_f32_e32 v66, v73, v191
	v_add_f32_e32 v192, v69, v64
	v_exp_f32_e32 v88, v66
	v_sub_f32_e32 v66, v74, v191
	v_pk_add_f32 v[64:65], v[164:165], v[192:193]
	v_exp_f32_e32 v166, v66
	v_sub_f32_e32 v66, v75, v191
	v_sub_f32_e32 v86, v92, v190
	v_pk_add_f32 v[64:65], v[168:169], v[64:65]
	v_exp_f32_e32 v170, v66
	v_sub_f32_e32 v66, v76, v191
	v_exp_f32_e32 v173, v86
	v_sub_f32_e32 v86, v93, v190
	v_pk_add_f32 v[64:65], v[158:159], v[64:65]
	v_exp_f32_e32 v172, v66
	v_sub_f32_e32 v66, v77, v191
	v_exp_f32_e32 v93, v86
	v_sub_f32_e32 v86, v94, v190
	v_pk_add_f32 v[64:65], v[88:89], v[64:65]
	v_exp_f32_e32 v92, v66
	v_sub_f32_e32 v66, v78, v191
	v_exp_f32_e32 v175, v86
	v_sub_f32_e32 v86, v95, v190
	v_pk_add_f32 v[64:65], v[166:167], v[64:65]
	v_exp_f32_e32 v174, v66
	v_sub_f32_e32 v66, v79, v191
	v_exp_f32_e32 v95, v86
	v_pk_add_f32 v[64:65], v[170:171], v[64:65]
	v_exp_f32_e32 v94, v66
	v_pk_add_f32 v[64:65], v[172:173], v[64:65]
	v_exp_f32_e32 v90, v90
	v_pk_add_f32 v[64:65], v[92:93], v[64:65]
	v_mov_b32_e32 v66, v91
	v_pk_add_f32 v[64:65], v[174:175], v[64:65]
	v_cvt_pk_bf16_f32 v83, v165, v169
	v_cvt_pk_bf16_f32 v84, v159, v89
	v_cvt_pk_bf16_f32 v85, v167, v171
	v_cvt_pk_bf16_f32 v86, v173, v93
	v_cvt_pk_bf16_f32 v87, v175, v95
	s_nop 0
	v_pk_add_f32 v[64:65], v[94:95], v[64:65]
	v_pk_mul_f32 v[46:47], v[46:47], v[66:67] op_sel_hi:[1,0]
	v_pk_mul_f32 v[44:45], v[44:45], v[66:67] op_sel_hi:[1,0]
	v_pk_mul_f32 v[42:43], v[42:43], v[66:67] op_sel_hi:[1,0]
	v_pk_mul_f32 v[40:41], v[40:41], v[66:67] op_sel_hi:[1,0]
	v_pk_mul_f32 v[38:39], v[38:39], v[66:67] op_sel_hi:[1,0]
	v_pk_mul_f32 v[36:37], v[36:37], v[66:67] op_sel_hi:[1,0]
	v_pk_mul_f32 v[34:35], v[34:35], v[66:67] op_sel_hi:[1,0]
	v_pk_mul_f32 v[32:33], v[32:33], v[66:67] op_sel_hi:[1,0]
	v_pk_mul_f32 v[62:63], v[62:63], v[66:67] op_sel_hi:[1,0]
	v_pk_mul_f32 v[60:61], v[60:61], v[66:67] op_sel_hi:[1,0]
	v_pk_mul_f32 v[58:59], v[58:59], v[66:67] op_sel_hi:[1,0]
	v_pk_mul_f32 v[56:57], v[56:57], v[66:67] op_sel_hi:[1,0]
	v_pk_mul_f32 v[54:55], v[54:55], v[66:67] op_sel_hi:[1,0]
	v_pk_mul_f32 v[52:53], v[52:53], v[66:67] op_sel_hi:[1,0]
	v_pk_mul_f32 v[50:51], v[50:51], v[66:67] op_sel_hi:[1,0]
	v_pk_mul_f32 v[48:49], v[48:49], v[66:67] op_sel_hi:[1,0]
	v_pk_fma_f32 v[148:149], v[148:149], v[90:91], v[64:65]
	v_cvt_pk_bf16_f32 v64, v194, v195
	v_cvt_pk_bf16_f32 v65, v196, v67
	v_cvt_pk_bf16_f32 v66, v68, v69
	v_cvt_pk_bf16_f32 v67, v164, v168
	v_cvt_pk_bf16_f32 v68, v158, v88
	v_cvt_pk_bf16_f32 v69, v166, v170
	v_cvt_pk_bf16_f32 v70, v172, v92
	v_cvt_pk_bf16_f32 v71, v174, v94
	ds_read2_b64 v[164:167], v188 offset1:2
	v_add_u32_e32 v201, 0x2000, v188
	ds_read2_b64 v[168:171], v201 offset0:32 offset1:34
	ds_read2_b64 v[172:175], v188 offset0:4 offset1:6
	ds_read2_b64 v[238:241], v201 offset0:36 offset1:38
	v_pk_mul_f32 v[30:31], v[30:31], v[90:91] op_sel_hi:[1,0]
	v_pk_mul_f32 v[28:29], v[28:29], v[90:91] op_sel_hi:[1,0]
	v_pk_mul_f32 v[26:27], v[26:27], v[90:91] op_sel_hi:[1,0]
	v_pk_mul_f32 v[24:25], v[24:25], v[90:91] op_sel_hi:[1,0]
	v_pk_mul_f32 v[22:23], v[22:23], v[90:91] op_sel_hi:[1,0]
	v_pk_mul_f32 v[20:21], v[20:21], v[90:91] op_sel_hi:[1,0]
	v_pk_mul_f32 v[18:19], v[18:19], v[90:91] op_sel_hi:[1,0]
	v_pk_mul_f32 v[16:17], v[16:17], v[90:91] op_sel_hi:[1,0]
	v_pk_mul_f32 v[14:15], v[14:15], v[90:91] op_sel_hi:[1,0]
	v_pk_mul_f32 v[12:13], v[12:13], v[90:91] op_sel_hi:[1,0]
	v_pk_mul_f32 v[10:11], v[10:11], v[90:91] op_sel_hi:[1,0]
	v_pk_mul_f32 v[8:9], v[8:9], v[90:91] op_sel_hi:[1,0]
	v_pk_mul_f32 v[6:7], v[6:7], v[90:91] op_sel_hi:[1,0]
	v_pk_mul_f32 v[4:5], v[4:5], v[90:91] op_sel_hi:[1,0]
	v_pk_mul_f32 v[2:3], v[2:3], v[90:91] op_sel_hi:[1,0]
	v_pk_mul_f32 v[0:1], v[0:1], v[90:91] op_sel_hi:[1,0]
	v_add_f32_e32 v190, v190, v199
	v_add_f32_e32 v191, v191, v200
	v_mul_f32_e32 v206, -1.0, v190
	v_mul_f32_e32 v222, -1.0, v191
	v_mov_b32_e32 v207, v206
	v_mov_b32_e32 v223, v222
	v_mov_b32_e32 v208, v206
	v_mov_b32_e32 v224, v222
	v_mov_b32_e32 v209, v206
	v_mov_b32_e32 v225, v222
	v_mov_b32_e32 v210, v206
	v_mov_b32_e32 v226, v222
	v_mov_b32_e32 v211, v206
	v_mov_b32_e32 v227, v222
	v_mov_b32_e32 v212, v206
	v_mov_b32_e32 v228, v222
	v_mov_b32_e32 v213, v206
	v_mov_b32_e32 v229, v222
	v_mov_b32_e32 v214, v206
	v_mov_b32_e32 v230, v222
	v_mov_b32_e32 v215, v206
	v_mov_b32_e32 v231, v222
	v_mov_b32_e32 v216, v206
	v_mov_b32_e32 v232, v222
	v_mov_b32_e32 v217, v206
	v_mov_b32_e32 v233, v222
	v_mov_b32_e32 v218, v206
	v_mov_b32_e32 v234, v222
	v_mov_b32_e32 v219, v206
	v_mov_b32_e32 v235, v222
	v_mov_b32_e32 v220, v206
	v_mov_b32_e32 v236, v222
	v_mov_b32_e32 v221, v206
	v_mov_b32_e32 v237, v222
.Latt_pv:
	s_setprio 1
	s_waitcnt lgkmcnt(3)
	v_mfma_f32_32x32x16_bf16 v[32:47], v[164:167], v[80:83], v[32:47]
	v_mfma_f32_32x32x16_bf16 v[16:31], v[164:167], v[64:67], v[16:31]
	s_waitcnt lgkmcnt(2)
	v_mfma_f32_32x32x16_bf16 v[48:63], v[168:171], v[80:83], v[48:63]
	v_mfma_f32_32x32x16_bf16 v[0:15], v[168:171], v[64:67], v[0:15]
	s_waitcnt lgkmcnt(1)
	v_mfma_f32_32x32x16_bf16 v[32:47], v[172:175], v[84:87], v[32:47]
	v_mfma_f32_32x32x16_bf16 v[16:31], v[172:175], v[68:71], v[16:31]
	s_waitcnt lgkmcnt(0)
	v_mfma_f32_32x32x16_bf16 v[48:63], v[238:241], v[84:87], v[48:63]
	v_mfma_f32_32x32x16_bf16 v[0:15], v[238:241], v[68:71], v[0:15]
	s_setprio 0
	s_branch .Latt_tail
